# speedup vs baseline: 1.0524x; 1.0016x over previous
; DI_ bf16x8 pack8(float a0, float a1, float a2, float a3, float a4, float a5, float a6, float a7) { u32x4 p; p.x = pk2(a0, a1); p.y = pk2(a2, a3); p.z = pk2(a4, a5); p.w = pk2(a6, a7); return __builtin_bit_cast(bf16x8, p); }
; #define MFMA32(a, b, c) __builtin_amdgcn_mfma_f32_32x32x16_bf16((a), (b), (c), 0, 0, 0)
; DI_ int kvmap(int rho) { return (rho & 0x13) | ((rho & 4) << 1) | ((rho & 8) >> 1); }
; DI_ void ssd_passC(const bf16_t* xsT, const bf16_t* Btok, const bf16_t* Ctok, const bf16_t* Sc, const float* dt, const float* acum, const float* Dskip, const float* norm_w, bf16_t* Z, unsigned char* lds, int tid, int lane, int wid) {
;     ...
;             for (int sb = 0; sb <= tb; ++sb) {
;                 f32x16 cb;
; #pragma unroll
;                 for (int i = 0; i < 16; ++i) cb[i] = 0.f;
;                 const unsigned char* bp = lds + PC_B + (32 * sb + kvmap(r32)) * PC_RS + hi * 16;
; #pragma unroll
;                 for (int ks = 0; ks < 8; ++ks) cb = MFMA32(*(const bf16x8*)(bp + 32 * ks), *(const bf16x8*)(cfp + 32 * ks), cb);
;                 float m[16];
; #pragma unroll
;                 for (int q4 = 0; q4 < 4; ++q4) {
;                     const int sl0 = 32 * sb + 16 * (q4 >> 1) + 8 * hi + 4 * (q4 & 1);
;                     const f32x4 as4 = *(const f32x4*)(sa + hl * 128 + sl0), ds4 = *(const f32x4*)(sd + hl * 128 + sl0);
; #pragma unroll
;                     for (int e = 0; e < 4; ++e) { const int sl = sl0 + e; float v = cb[4 * q4 + e] * __expf(fminf(at - as4[e], 0.f)) * ds4[e]; v = (sl <= tl) ? v : 0.f; if (sl == tl) v += Dh; m[4 * q4 + e] = v; }
;                 }
;                 const bf16x8 pf0 = pack8(m[0], m[1], m[2], m[3], m[4], m[5], m[6], m[7]), pf1 = pack8(m[8], m[9], m[10], m[11], m[12], m[13], m[14], m[15]);
.LBB0_765:
	v_add_u32_e32 v106, 0, v99
	ds_read_b128 v[206:209], v106
	ds_read_b128 v[210:213], v106 offset:32
	ds_read_b128 v[214:217], v106 offset:64
	ds_read_b128 v[218:221], v106 offset:96
	ds_read_b128 v[222:225], v106 offset:128
	ds_read_b128 v[226:229], v106 offset:160
	ds_read_b128 v[230:233], v106 offset:192
	ds_read_b128 v[234:237], v106 offset:224
	v_add_u32_e32 v111, 0, v100
	v_add_u32_e32 v106, 0x22800, v111
	ds_read_b128 v[106:109], v106
	v_add_u32_e32 v102, 0x22000, v111
	ds_read_b128 v[102:105], v102
	v_add_u32_e32 v110, s7, v137
	v_cmp_gt_u32_e32 vcc, v90, v110
	s_waitcnt lgkmcnt(9)
	v_mfma_f32_32x32x16_bf16 v[32:47], v[206:209], v[50:53], 0
	v_cmp_le_u32_e64 s[0:1], v110, v90
	v_add_u32_e32 v112, 4, v110
	s_add_i32 s7, s7, 32
	v_add_u32_e32 v100, 0x80, v100
	v_add_u32_e32 v99, 0x2200, v99
	s_cmp_lg_u32 s18, s7
	s_waitcnt lgkmcnt(8)
	v_mfma_f32_32x32x16_bf16 v[32:47], v[210:213], v[54:57], v[32:47]
	s_waitcnt lgkmcnt(7)
	v_mfma_f32_32x32x16_bf16 v[32:47], v[214:217], v[58:61], v[32:47]
	s_waitcnt lgkmcnt(6)
	v_mfma_f32_32x32x16_bf16 v[32:47], v[218:221], v[62:65], v[32:47]
	s_waitcnt lgkmcnt(5)
	v_mfma_f32_32x32x16_bf16 v[32:47], v[222:225], v[66:69], v[32:47]
	s_waitcnt lgkmcnt(4)
	v_mfma_f32_32x32x16_bf16 v[32:47], v[226:229], v[70:73], v[32:47]
	s_waitcnt lgkmcnt(3)
	v_mfma_f32_32x32x16_bf16 v[32:47], v[230:233], v[74:77], v[32:47]
	s_waitcnt lgkmcnt(2)
	v_mfma_f32_32x32x16_bf16 v[32:47], v[234:237], v[78:81], v[32:47]
	v_add_u32_e32 v222, 0x11000, v101
	ds_read_b128 v[206:209], v222
	ds_read_b128 v[210:213], v222 offset:32
	v_add_u32_e32 v222, 0x13200, v101
	ds_read_b128 v[214:217], v222
	ds_read_b128 v[218:221], v222 offset:32
	s_waitcnt lgkmcnt(0)
	v_sub_f32_e32 v102, v98, v102
	v_sub_f32_e32 v103, v98, v103
	v_min_f32_e32 v102, 0, v102
	v_min_f32_e32 v103, 0, v103
	v_mul_f32_e32 v102, 0x3fb8aa3b, v102
	v_mul_f32_e32 v103, 0x3fb8aa3b, v103
	v_exp_f32_e32 v102, v102
	v_exp_f32_e32 v103, v103
	s_nop 0
	v_mul_f32_e32 v32, v32, v102
	v_mul_f32_e32 v33, v33, v103
	v_mul_f32_e32 v32, v106, v32
	v_mul_f32_e32 v103, v107, v33
	v_add_u32_e32 v102, 1, v110
	v_cndmask_b32_e64 v33, 0, v32, s[0:1]
	v_cndmask_b32_e32 v32, 0, v103, vcc
	v_cmp_eq_u32_e32 vcc, v110, v90
	v_cmp_eq_u32_e64 s[0:1], v102, v49
	v_pk_add_f32 v[102:103], v[96:97], v[32:33]
	s_nop 0
	v_cndmask_b32_e64 v106, v32, v102, s[0:1]
	v_cndmask_b32_e32 v107, v33, v103, vcc
	v_sub_f32_e32 v32, v98, v104
	v_sub_f32_e32 v33, v98, v105
	v_min_f32_e32 v32, 0, v32
	v_min_f32_e32 v33, 0, v33
	v_mul_f32_e32 v32, 0x3fb8aa3b, v32
	v_mul_f32_e32 v33, 0x3fb8aa3b, v33
	v_exp_f32_e32 v32, v32
	v_exp_f32_e32 v33, v33
	v_or_b32_e32 v102, 3, v110
	v_or_b32_e32 v103, 2, v110
	v_cmp_le_u32_e32 vcc, v102, v49
	v_pk_mul_f32 v[32:33], v[34:35], v[32:33]
	v_cmp_eq_u32_e64 s[0:1], v102, v49
	v_pk_mul_f32 v[32:33], v[108:109], v[32:33]
	v_add_u32_e32 v102, 0x22810, v111
	v_cndmask_b32_e32 v33, 0, v33, vcc
	v_cmp_le_u32_e32 vcc, v103, v90
	s_nop 1
	v_cndmask_b32_e32 v32, 0, v32, vcc
	v_cmp_eq_u32_e32 vcc, v103, v90
	v_pk_add_f32 v[34:35], v[96:97], v[32:33]
	ds_read_b128 v[102:105], v102
	v_cndmask_b32_e32 v109, v32, v34, vcc
	v_add_u32_e32 v32, 0x22010, v111
	v_cndmask_b32_e64 v108, v33, v35, s[0:1]
	ds_read_b128 v[32:35], v32
	v_cmp_gt_u32_e32 vcc, v90, v112
	v_cmp_le_u32_e64 s[0:1], v112, v90
	s_waitcnt lgkmcnt(0)
	v_sub_f32_e32 v32, v98, v32
	v_sub_f32_e32 v33, v98, v33
	v_min_f32_e32 v32, 0, v32
	v_min_f32_e32 v33, 0, v33
	v_mul_f32_e32 v32, 0x3fb8aa3b, v32
	v_mul_f32_e32 v33, 0x3fb8aa3b, v33
	v_exp_f32_e32 v32, v32
	v_exp_f32_e32 v33, v33
	v_mul_f32_e32 v32, v36, v32
	v_mul_f32_e32 v33, v37, v33
	v_mul_f32_e32 v32, v102, v32
	v_mul_f32_e32 v37, v103, v33
	v_add_u32_e32 v36, 5, v110
	v_cndmask_b32_e64 v33, 0, v32, s[0:1]
	v_cndmask_b32_e32 v32, 0, v37, vcc
	v_cmp_eq_u32_e32 vcc, v112, v90
	v_cmp_eq_u32_e64 s[0:1], v36, v49
	v_pk_add_f32 v[36:37], v[96:97], v[32:33]
	s_nop 0
	v_cndmask_b32_e64 v102, v32, v36, s[0:1]
	v_cndmask_b32_e32 v103, v33, v37, vcc
	v_sub_f32_e32 v32, v98, v34
	v_sub_f32_e32 v33, v98, v35
	v_min_f32_e32 v32, 0, v32
	v_min_f32_e32 v33, 0, v33
	v_mul_f32_e32 v32, 0x3fb8aa3b, v32
	v_mul_f32_e32 v33, 0x3fb8aa3b, v33
	v_exp_f32_e32 v32, v32
	v_exp_f32_e32 v33, v33
	v_or_b32_e32 v34, 3, v112
	v_or_b32_e32 v35, 2, v112
	v_cmp_le_u32_e32 vcc, v34, v49
	v_pk_mul_f32 v[32:33], v[38:39], v[32:33]
	v_cmp_eq_u32_e64 s[0:1], v34, v49
	v_pk_mul_f32 v[32:33], v[104:105], v[32:33]
	v_add_u32_e32 v36, 0x22840, v111
	v_cndmask_b32_e32 v33, 0, v33, vcc
	v_cmp_le_u32_e32 vcc, v35, v90
	ds_read_b128 v[36:39], v36
	v_add_u32_e32 v112, 16, v110
	v_cndmask_b32_e32 v32, 0, v32, vcc
	v_cmp_eq_u32_e32 vcc, v35, v90
	v_pk_add_f32 v[34:35], v[96:97], v[32:33]
	s_nop 0
	v_cndmask_b32_e32 v105, v32, v34, vcc
	v_add_u32_e32 v32, 0x22040, v111
	v_cndmask_b32_e64 v104, v33, v35, s[0:1]
	ds_read_b128 v[32:35], v32
	v_cmp_gt_u32_e32 vcc, v90, v112
	v_cmp_le_u32_e64 s[0:1], v112, v90
	s_waitcnt lgkmcnt(0)
; DI_ float bf_lo(unsigned w) { return __uint_as_float(w << 16); }
; DI_ float bf_hi(unsigned w) { return __uint_as_float(w & 0xffff0000u); }
; DI_ bf16x8 pack8(float a0, float a1, float a2, float a3, float a4, float a5, float a6, float a7) { u32x4 p; p.x = pk2(a0, a1); p.y = pk2(a2, a3); p.z = pk2(a4, a5); p.w = pk2(a6, a7); return __builtin_bit_cast(bf16x8, p); }
; #define MFMA32(a, b, c) __builtin_amdgcn_mfma_f32_32x32x16_bf16((a), (b), (c), 0, 0, 0)
; DI_ float silu_f(float v) { return v / (1.f + __expf(-v)); }
; DI_ void ssd_passC(const bf16_t* xsT, const bf16_t* Btok, const bf16_t* Ctok, const bf16_t* Sc, const float* dt, const float* acum, const float* Dskip, const float* norm_w, bf16_t* Z, unsigned char* lds, int tid, int lane, int wid) {
;     ...
;                     for (int e = 0; e < 4; ++e) { const int sl = sl0 + e; float v = cb[4 * q4 + e] * __expf(fminf(at - as4[e], 0.f)) * ds4[e]; v = (sl <= tl) ? v : 0.f; if (sl == tl) v += Dh; m[4 * q4 + e] = v; }
;                 }
;                 const bf16x8 pf0 = pack8(m[0], m[1], m[2], m[3], m[4], m[5], m[6], m[7]), pf1 = pack8(m[8], m[9], m[10], m[11], m[12], m[13], m[14], m[15]);
; #pragma unroll
;                 for (int pb = 0; pb < 2; ++pb) {
;                     const unsigned char* xp = lds + PC_X + (hl * 64 + 32 * pb + r32) * PC_RS + (32 * sb + 8 * hi) * 2;
;                     yv[it][pb] = MFMA32(*(const bf16x8*)xp, pf0, yv[it][pb]); yv[it][pb] = MFMA32(*(const bf16x8*)(xp + 32), pf1, yv[it][pb]);
;                 }
;     ...
;             const int tg = t0 + tl; float sq = 0.f;
; #pragma unroll
;             for (int pb = 0; pb < 2; ++pb)
; #pragma unroll
;                 for (int q4 = 0; q4 < 4; ++q4) {
;                     const int chn = hh * 64 + 32 * pb + 8 * q4 + 4 * hi;
;                     const u32x2 zw = *(const u32x2*)(Z + (size_t)tg * DI + chn);
;                     const float a0 = yv[it][pb][4 * q4] * silu_f(bf_lo(zw.x)), a1 = yv[it][pb][4 * q4 + 1] * silu_f(bf_hi(zw.x)), a2 = yv[it][pb][4 * q4 + 2] * silu_f(bf_lo(zw.y)), a3 = yv[it][pb][4 * q4 + 3] * silu_f(bf_hi(zw.y));
;                     sq += (a0 * a0 + a1 * a1) + (a2 * a2 + a3 * a3);
;                     yv[it][pb][4 * q4] = a0; yv[it][pb][4 * q4 + 1] = a1; yv[it][pb][4 * q4 + 2] = a2; yv[it][pb][4 * q4 + 3] = a3;
	v_sub_f32_e32 v32, v98, v32
	v_sub_f32_e32 v33, v98, v33
	v_min_f32_e32 v32, 0, v32
	v_min_f32_e32 v33, 0, v33
	v_mul_f32_e32 v32, 0x3fb8aa3b, v32
	v_mul_f32_e32 v33, 0x3fb8aa3b, v33
	v_exp_f32_e32 v32, v32
	v_exp_f32_e32 v33, v33
	v_mul_f32_e32 v32, v40, v32
	v_mul_f32_e32 v33, v41, v33
	v_mul_f32_e32 v32, v36, v32
	v_mul_f32_e32 v37, v37, v33
	v_add_u32_e32 v36, 17, v110
	v_cndmask_b32_e64 v33, 0, v32, s[0:1]
	v_cndmask_b32_e32 v32, 0, v37, vcc
	v_cmp_eq_u32_e32 vcc, v112, v90
	v_cmp_eq_u32_e64 s[0:1], v36, v49
	v_pk_add_f32 v[36:37], v[96:97], v[32:33]
	s_nop 0
	v_cndmask_b32_e64 v40, v32, v36, s[0:1]
	v_cndmask_b32_e32 v41, v33, v37, vcc
	v_sub_f32_e32 v32, v98, v34
	v_sub_f32_e32 v33, v98, v35
	v_min_f32_e32 v32, 0, v32
	v_min_f32_e32 v33, 0, v33
	v_mul_f32_e32 v32, 0x3fb8aa3b, v32
	v_mul_f32_e32 v33, 0x3fb8aa3b, v33
	v_exp_f32_e32 v32, v32
	v_exp_f32_e32 v33, v33
	v_or_b32_e32 v34, 3, v112
	v_or_b32_e32 v35, 2, v112
	v_cmp_le_u32_e32 vcc, v34, v49
	v_pk_mul_f32 v[32:33], v[42:43], v[32:33]
	v_cmp_eq_u32_e64 s[0:1], v34, v49
	v_pk_mul_f32 v[32:33], v[38:39], v[32:33]
	v_add_u32_e32 v36, 0x22850, v111
	v_cndmask_b32_e32 v33, 0, v33, vcc
	v_cmp_le_u32_e32 vcc, v35, v90
	ds_read_b128 v[36:39], v36
	v_add_u32_e32 v112, 20, v110
	v_cndmask_b32_e32 v32, 0, v32, vcc
	v_cmp_eq_u32_e32 vcc, v35, v90
	v_pk_add_f32 v[34:35], v[96:97], v[32:33]
	s_nop 0
	v_cndmask_b32_e32 v43, v32, v34, vcc
	v_add_u32_e32 v32, 0x22050, v111
	v_cndmask_b32_e64 v42, v33, v35, s[0:1]
	ds_read_b128 v[32:35], v32
	v_cmp_gt_u32_e32 vcc, v90, v112
	v_cmp_le_u32_e64 s[0:1], v112, v90
	s_waitcnt lgkmcnt(0)
	v_sub_f32_e32 v32, v98, v32
	v_sub_f32_e32 v33, v98, v33
	v_min_f32_e32 v32, 0, v32
	v_min_f32_e32 v33, 0, v33
	v_mul_f32_e32 v32, 0x3fb8aa3b, v32
	v_mul_f32_e32 v33, 0x3fb8aa3b, v33
	v_exp_f32_e32 v32, v32
	v_exp_f32_e32 v33, v33
	v_mul_f32_e32 v32, v44, v32
	v_mul_f32_e32 v33, v45, v33
	v_mul_f32_e32 v32, v36, v32
	v_mul_f32_e32 v37, v37, v33
	v_add_u32_e32 v36, 21, v110
	v_cndmask_b32_e64 v33, 0, v32, s[0:1]
	v_cndmask_b32_e32 v32, 0, v37, vcc
	v_cmp_eq_u32_e32 vcc, v112, v90
	v_cmp_eq_u32_e64 s[0:1], v36, v49
	v_pk_add_f32 v[36:37], v[96:97], v[32:33]
	s_nop 0
	v_cndmask_b32_e64 v44, v32, v36, s[0:1]
	v_cndmask_b32_e32 v45, v33, v37, vcc
	v_sub_f32_e32 v32, v98, v34
	v_sub_f32_e32 v33, v98, v35
	v_min_f32_e32 v32, 0, v32
	v_min_f32_e32 v33, 0, v33
	v_mul_f32_e32 v32, 0x3fb8aa3b, v32
	v_mul_f32_e32 v33, 0x3fb8aa3b, v33
	v_exp_f32_e32 v32, v32
	v_exp_f32_e32 v33, v33
	v_or_b32_e32 v34, 3, v112
	v_or_b32_e32 v35, 2, v112
	v_cmp_le_u32_e32 vcc, v34, v49
	v_pk_mul_f32 v[32:33], v[46:47], v[32:33]
	v_cmp_eq_u32_e64 s[0:1], v34, v49
	v_pk_mul_f32 v[32:33], v[38:39], v[32:33]
	v_cvt_pk_bf16_f32 v36, v107, v106
	v_cndmask_b32_e32 v33, 0, v33, vcc
	v_cmp_le_u32_e32 vcc, v35, v90
	v_cvt_pk_bf16_f32 v37, v109, v108
	v_cvt_pk_bf16_f32 v38, v103, v102
	v_cndmask_b32_e32 v32, 0, v32, vcc
	v_cmp_eq_u32_e32 vcc, v35, v90
	v_pk_add_f32 v[34:35], v[96:97], v[32:33]
	v_cvt_pk_bf16_f32 v39, v105, v104
	v_cndmask_b32_e32 v46, v32, v34, vcc
	v_cvt_pk_bf16_f32 v34, v45, v44
	v_cvt_pk_bf16_f32 v32, v41, v40
	v_cndmask_b32_e64 v35, v33, v35, s[0:1]
	v_cvt_pk_bf16_f32 v33, v43, v42
	s_waitcnt lgkmcnt(0)
	v_mfma_f32_32x32x16_bf16 v[16:31], v[206:209], v[36:39], v[16:31]
	v_cvt_pk_bf16_f32 v35, v46, v35
	v_add_u32_e32 v101, 64, v101
	s_waitcnt lgkmcnt(0)
	v_mfma_f32_32x32x16_bf16 v[16:31], v[210:213], v[32:35], v[16:31]
	s_waitcnt lgkmcnt(0)
	v_mfma_f32_32x32x16_bf16 v[0:15], v[214:217], v[36:39], v[0:15]
	s_waitcnt lgkmcnt(0)
	v_mfma_f32_32x32x16_bf16 v[0:15], v[218:221], v[32:35], v[0:15]
	s_cbranch_scc1 .LBB0_765
	v_or_b32_e32 v102, s42, v90
	v_ashrrev_i32_e32 v103, 31, v102
	v_lshl_or_b32 v96, s6, 6, v138
	v_lshlrev_b64 v[32:33], 12, v[102:103]
	v_lshl_add_u64 v[32:33], s[56:57], 0, v[32:33]
	v_ashrrev_i32_e32 v97, 31, v96
	v_lshl_add_u64 v[32:33], v[96:97], 1, v[32:33]
	global_load_dwordx2 v[206:207], v[32:33], off
	global_load_dwordx2 v[208:209], v[32:33], off offset:16
	global_load_dwordx2 v[210:211], v[32:33], off offset:32
	global_load_dwordx2 v[212:213], v[32:33], off offset:48
	global_load_dwordx2 v[214:215], v[32:33], off offset:64
	global_load_dwordx2 v[216:217], v[32:33], off offset:80
	global_load_dwordx2 v[218:219], v[32:33], off offset:96
	global_load_dwordx2 v[220:221], v[32:33], off offset:112
	s_waitcnt vmcnt(7)
	v_mov_b32_e32 v34, v206
	v_mov_b32_e32 v35, v207
	v_lshlrev_b32_e32 v38, 16, v34
	v_and_b32_e32 v34, 0xffff0000, v34
	v_mul_f32_e32 v36, 0xbfb8aa3b, v38
	v_mul_f32_e32 v37, 0xbfb8aa3b, v34
	v_exp_f32_e32 v36, v36
	v_exp_f32_e32 v37, v37
	s_nop 0
	v_pk_add_f32 v[36:37], v[36:37], 1.0 op_sel_hi:[1,0]
	s_nop 0
	v_rcp_f32_e32 v40, v37
	s_nop 0
	v_mul_f32_e32 v37, v34, v40
	v_rcp_f32_e32 v39, v36
	s_nop 0
	v_mul_f32_e32 v36, v38, v39
	v_lshlrev_b32_e32 v34, 16, v35
	v_and_b32_e32 v35, 0xffff0000, v35
	v_pk_mul_f32 v[98:99], v[16:17], v[36:37]
	v_mul_f32_e32 v16, 0xbfb8aa3b, v34
	v_mul_f32_e32 v17, 0xbfb8aa3b, v35
	v_exp_f32_e32 v16, v16
	v_exp_f32_e32 v17, v17
	s_nop 0
	v_pk_add_f32 v[16:17], v[16:17], 1.0 op_sel_hi:[1,0]
	s_nop 0
	v_rcp_f32_e32 v37, v17
	s_nop 0
	v_mul_f32_e32 v17, v35, v37
	v_rcp_f32_e32 v36, v16
	s_nop 0
	v_mul_f32_e32 v16, v34, v36
	v_pk_mul_f32 v[100:101], v[18:19], v[16:17]
	v_pk_mul_f32 v[16:17], v[98:99], v[98:99]
	v_pk_mul_f32 v[18:19], v[100:101], v[100:101]
	v_add_f32_e32 v16, v16, v17
	v_add_f32_e32 v18, v18, v19
	v_add_f32_e32 v16, v16, v18
	s_waitcnt vmcnt(6)
; DI_ float bf_lo(unsigned w) { return __uint_as_float(w << 16); }
; DI_ float bf_hi(unsigned w) { return __uint_as_float(w & 0xffff0000u); }
; DI_ float silu_f(float v) { return v / (1.f + __expf(-v)); }
; DI_ void ssd_passC(const bf16_t* xsT, const bf16_t* Btok, const bf16_t* Ctok, const bf16_t* Sc, const float* dt, const float* acum, const float* Dskip, const float* norm_w, bf16_t* Z, unsigned char* lds, int tid, int lane, int wid) {
;     ...
;             const int tg = t0 + tl; float sq = 0.f;
; #pragma unroll
;             for (int pb = 0; pb < 2; ++pb)
; #pragma unroll
;                 for (int q4 = 0; q4 < 4; ++q4) {
;                     const int chn = hh * 64 + 32 * pb + 8 * q4 + 4 * hi;
;                     const u32x2 zw = *(const u32x2*)(Z + (size_t)tg * DI + chn);
;                     const float a0 = yv[it][pb][4 * q4] * silu_f(bf_lo(zw.x)), a1 = yv[it][pb][4 * q4 + 1] * silu_f(bf_hi(zw.x)), a2 = yv[it][pb][4 * q4 + 2] * silu_f(bf_lo(zw.y)), a3 = yv[it][pb][4 * q4 + 3] * silu_f(bf_hi(zw.y));
;                     sq += (a0 * a0 + a1 * a1) + (a2 * a2 + a3 * a3);
;                     yv[it][pb][4 * q4] = a0; yv[it][pb][4 * q4 + 1] = a1; yv[it][pb][4 * q4 + 2] = a2; yv[it][pb][4 * q4 + 3] = a3;
	v_mov_b32_e32 v34, v208
	v_mov_b32_e32 v35, v209
	v_lshlrev_b32_e32 v38, 16, v34
	v_and_b32_e32 v34, 0xffff0000, v34
	v_mul_f32_e32 v36, 0xbfb8aa3b, v38
	v_mul_f32_e32 v37, 0xbfb8aa3b, v34
	v_exp_f32_e32 v36, v36
	v_exp_f32_e32 v37, v37
	s_nop 0
	v_pk_add_f32 v[36:37], v[36:37], 1.0 op_sel_hi:[1,0]
	s_nop 0
	v_rcp_f32_e32 v40, v37
	s_nop 0
	v_mul_f32_e32 v37, v34, v40
	v_rcp_f32_e32 v39, v36
	s_nop 0
	v_mul_f32_e32 v36, v38, v39
	v_lshlrev_b32_e32 v34, 16, v35
	v_and_b32_e32 v35, 0xffff0000, v35
	v_pk_mul_f32 v[104:105], v[20:21], v[36:37]
	v_mul_f32_e32 v20, 0xbfb8aa3b, v34
	v_mul_f32_e32 v21, 0xbfb8aa3b, v35
	v_exp_f32_e32 v20, v20
	v_exp_f32_e32 v21, v21
	s_nop 0
	v_pk_add_f32 v[20:21], v[20:21], 1.0 op_sel_hi:[1,0]
	s_nop 0
	v_rcp_f32_e32 v37, v21
	s_nop 0
	v_mul_f32_e32 v21, v35, v37
	v_rcp_f32_e32 v36, v20
	s_nop 0
	v_mul_f32_e32 v20, v34, v36
	v_pk_mul_f32 v[106:107], v[22:23], v[20:21]
	v_pk_mul_f32 v[20:21], v[104:105], v[104:105]
	v_pk_mul_f32 v[22:23], v[106:107], v[106:107]
	v_add_f32_e32 v20, v20, v21
	v_add_f32_e32 v22, v22, v23
	v_add_f32_e32 v20, v20, v22
	v_add_f32_e32 v16, v16, v20
	s_waitcnt vmcnt(5)
	v_mov_b32_e32 v34, v210
	v_mov_b32_e32 v35, v211
	v_lshlrev_b32_e32 v38, 16, v34
	v_and_b32_e32 v34, 0xffff0000, v34
	v_mul_f32_e32 v36, 0xbfb8aa3b, v38
	v_mul_f32_e32 v37, 0xbfb8aa3b, v34
	v_exp_f32_e32 v36, v36
	v_exp_f32_e32 v37, v37
	s_nop 0
	v_pk_add_f32 v[36:37], v[36:37], 1.0 op_sel_hi:[1,0]
	s_nop 0
	v_rcp_f32_e32 v40, v37
	s_nop 0
	v_mul_f32_e32 v37, v34, v40
	v_rcp_f32_e32 v39, v36
	s_nop 0
	v_mul_f32_e32 v36, v38, v39
	v_lshlrev_b32_e32 v34, 16, v35
	v_and_b32_e32 v35, 0xffff0000, v35
	v_pk_mul_f32 v[108:109], v[24:25], v[36:37]
	v_mul_f32_e32 v24, 0xbfb8aa3b, v34
	v_mul_f32_e32 v25, 0xbfb8aa3b, v35
	v_exp_f32_e32 v24, v24
	v_exp_f32_e32 v25, v25
	s_nop 0
	v_pk_add_f32 v[24:25], v[24:25], 1.0 op_sel_hi:[1,0]
	s_nop 0
	v_rcp_f32_e32 v37, v25
	s_nop 0
	v_mul_f32_e32 v25, v35, v37
	v_rcp_f32_e32 v36, v24
	s_nop 0
	v_mul_f32_e32 v24, v34, v36
	v_pk_mul_f32 v[110:111], v[26:27], v[24:25]
	v_pk_mul_f32 v[24:25], v[108:109], v[108:109]
	v_pk_mul_f32 v[26:27], v[110:111], v[110:111]
	v_add_f32_e32 v18, v24, v25
	v_add_f32_e32 v17, v26, v27
	v_add_f32_e32 v17, v18, v17
	v_add_f32_e32 v16, v16, v17
	s_waitcnt vmcnt(4)
	v_mov_b32_e32 v34, v212
	v_mov_b32_e32 v35, v213
	v_lshlrev_b32_e32 v38, 16, v34
	v_and_b32_e32 v34, 0xffff0000, v34
	v_mul_f32_e32 v36, 0xbfb8aa3b, v38
	v_mul_f32_e32 v37, 0xbfb8aa3b, v34
	v_exp_f32_e32 v36, v36
	v_exp_f32_e32 v37, v37
	s_nop 0
	v_pk_add_f32 v[36:37], v[36:37], 1.0 op_sel_hi:[1,0]
	s_nop 0
	v_rcp_f32_e32 v40, v37
	s_nop 0
	v_mul_f32_e32 v37, v34, v40
	v_rcp_f32_e32 v39, v36
	s_nop 0
	v_mul_f32_e32 v36, v38, v39
	v_lshlrev_b32_e32 v34, 16, v35
	v_and_b32_e32 v35, 0xffff0000, v35
	v_pk_mul_f32 v[112:113], v[28:29], v[36:37]
	v_mul_f32_e32 v28, 0xbfb8aa3b, v34
	v_mul_f32_e32 v29, 0xbfb8aa3b, v35
	v_exp_f32_e32 v28, v28
	v_exp_f32_e32 v29, v29
	s_nop 0
	v_pk_add_f32 v[28:29], v[28:29], 1.0 op_sel_hi:[1,0]
	s_nop 0
	v_rcp_f32_e32 v37, v29
	s_nop 0
	v_mul_f32_e32 v29, v35, v37
	v_rcp_f32_e32 v36, v28
	s_nop 0
	v_mul_f32_e32 v28, v34, v36
	v_pk_mul_f32 v[114:115], v[30:31], v[28:29]
	v_pk_mul_f32 v[28:29], v[112:113], v[112:113]
	v_pk_mul_f32 v[30:31], v[114:115], v[114:115]
	v_add_f32_e32 v18, v28, v29
	v_add_f32_e32 v17, v30, v31
	v_add_f32_e32 v17, v18, v17
	v_add_f32_e32 v16, v16, v17
	s_waitcnt vmcnt(3)
	v_mov_b32_e32 v34, v214
	v_mov_b32_e32 v35, v215
	v_lshlrev_b32_e32 v38, 16, v34
	v_and_b32_e32 v34, 0xffff0000, v34
	v_mul_f32_e32 v36, 0xbfb8aa3b, v38
	v_mul_f32_e32 v37, 0xbfb8aa3b, v34
	v_exp_f32_e32 v36, v36
	v_exp_f32_e32 v37, v37
	s_nop 0
	v_pk_add_f32 v[36:37], v[36:37], 1.0 op_sel_hi:[1,0]
	s_nop 0
	v_rcp_f32_e32 v40, v37
	s_nop 0
	v_mul_f32_e32 v37, v34, v40
	v_rcp_f32_e32 v39, v36
	s_nop 0
	v_mul_f32_e32 v36, v38, v39
	v_lshlrev_b32_e32 v34, 16, v35
	v_and_b32_e32 v35, 0xffff0000, v35
	v_pk_mul_f32 v[116:117], v[0:1], v[36:37]
	v_mul_f32_e32 v0, 0xbfb8aa3b, v34
	v_mul_f32_e32 v1, 0xbfb8aa3b, v35
	v_exp_f32_e32 v0, v0
	v_exp_f32_e32 v1, v1
	s_nop 0
	v_pk_add_f32 v[0:1], v[0:1], 1.0 op_sel_hi:[1,0]
	s_nop 0
	v_rcp_f32_e32 v37, v1
	s_nop 0
	v_mul_f32_e32 v1, v35, v37
	v_rcp_f32_e32 v36, v0
	s_nop 0
	v_mul_f32_e32 v0, v34, v36
	v_pk_mul_f32 v[118:119], v[2:3], v[0:1]
	v_pk_mul_f32 v[0:1], v[116:117], v[116:117]
	v_pk_mul_f32 v[2:3], v[118:119], v[118:119]
	v_add_f32_e32 v0, v0, v1
	v_add_f32_e32 v2, v2, v3
	v_add_f32_e32 v0, v0, v2
	v_add_f32_e32 v0, v16, v0
	s_waitcnt vmcnt(2)
; DI_ float bf_lo(unsigned w) { return __uint_as_float(w << 16); }
; DI_ float bf_hi(unsigned w) { return __uint_as_float(w & 0xffff0000u); }
; DI_ float silu_f(float v) { return v / (1.f + __expf(-v)); }
; DI_ void ssd_passC(const bf16_t* xsT, const bf16_t* Btok, const bf16_t* Ctok, const bf16_t* Sc, const float* dt, const float* acum, const float* Dskip, const float* norm_w, bf16_t* Z, unsigned char* lds, int tid, int lane, int wid) {
;     ...
;             const int tg = t0 + tl; float sq = 0.f;
; #pragma unroll
;             for (int pb = 0; pb < 2; ++pb)
; #pragma unroll
;                 for (int q4 = 0; q4 < 4; ++q4) {
;                     const int chn = hh * 64 + 32 * pb + 8 * q4 + 4 * hi;
;                     const u32x2 zw = *(const u32x2*)(Z + (size_t)tg * DI + chn);
;                     const float a0 = yv[it][pb][4 * q4] * silu_f(bf_lo(zw.x)), a1 = yv[it][pb][4 * q4 + 1] * silu_f(bf_hi(zw.x)), a2 = yv[it][pb][4 * q4 + 2] * silu_f(bf_lo(zw.y)), a3 = yv[it][pb][4 * q4 + 3] * silu_f(bf_hi(zw.y));
;                     sq += (a0 * a0 + a1 * a1) + (a2 * a2 + a3 * a3);
;                     yv[it][pb][4 * q4] = a0; yv[it][pb][4 * q4 + 1] = a1; yv[it][pb][4 * q4 + 2] = a2; yv[it][pb][4 * q4 + 3] = a3;
;                 }
;             sq += __shfl_xor(sq, 32);
;             if (hi == 0) ex[hl * 128 + tl] = sq;
	v_mov_b32_e32 v34, v216
	v_mov_b32_e32 v35, v217
	v_lshlrev_b32_e32 v38, 16, v34
	v_and_b32_e32 v34, 0xffff0000, v34
	v_mul_f32_e32 v36, 0xbfb8aa3b, v38
	v_mul_f32_e32 v37, 0xbfb8aa3b, v34
	v_exp_f32_e32 v36, v36
	v_exp_f32_e32 v37, v37
	s_nop 0
	v_pk_add_f32 v[36:37], v[36:37], 1.0 op_sel_hi:[1,0]
	s_nop 0
	v_rcp_f32_e32 v40, v37
	s_nop 0
	v_mul_f32_e32 v37, v34, v40
	v_rcp_f32_e32 v39, v36
	s_nop 0
	v_mul_f32_e32 v36, v38, v39
	v_lshlrev_b32_e32 v34, 16, v35
	v_and_b32_e32 v35, 0xffff0000, v35
	v_pk_mul_f32 v[120:121], v[4:5], v[36:37]
	v_mul_f32_e32 v4, 0xbfb8aa3b, v34
	v_mul_f32_e32 v5, 0xbfb8aa3b, v35
	v_exp_f32_e32 v4, v4
	v_exp_f32_e32 v5, v5
	s_nop 0
	v_pk_add_f32 v[4:5], v[4:5], 1.0 op_sel_hi:[1,0]
	s_nop 0
	v_rcp_f32_e32 v37, v5
	s_nop 0
	v_mul_f32_e32 v5, v35, v37
	v_rcp_f32_e32 v36, v4
	s_nop 0
	v_mul_f32_e32 v4, v34, v36
	v_pk_mul_f32 v[122:123], v[6:7], v[4:5]
	v_pk_mul_f32 v[4:5], v[120:121], v[120:121]
	v_pk_mul_f32 v[6:7], v[122:123], v[122:123]
	v_add_f32_e32 v2, v4, v5
	v_add_f32_e32 v1, v6, v7
	v_add_f32_e32 v1, v2, v1
	v_add_f32_e32 v0, v0, v1
	s_waitcnt vmcnt(1)
	v_mov_b32_e32 v34, v218
	v_mov_b32_e32 v35, v219
	v_lshlrev_b32_e32 v38, 16, v34
	v_and_b32_e32 v34, 0xffff0000, v34
	v_mul_f32_e32 v36, 0xbfb8aa3b, v38
	v_mul_f32_e32 v37, 0xbfb8aa3b, v34
	v_exp_f32_e32 v36, v36
	v_exp_f32_e32 v37, v37
	s_nop 0
	v_pk_add_f32 v[36:37], v[36:37], 1.0 op_sel_hi:[1,0]
	s_nop 0
	v_rcp_f32_e32 v40, v37
	s_nop 0
	v_mul_f32_e32 v37, v34, v40
	v_rcp_f32_e32 v39, v36
	s_nop 0
	v_mul_f32_e32 v36, v38, v39
	v_lshlrev_b32_e32 v34, 16, v35
	v_and_b32_e32 v35, 0xffff0000, v35
	v_pk_mul_f32 v[124:125], v[8:9], v[36:37]
	v_mul_f32_e32 v8, 0xbfb8aa3b, v34
	v_mul_f32_e32 v9, 0xbfb8aa3b, v35
	v_exp_f32_e32 v8, v8
	v_exp_f32_e32 v9, v9
	s_nop 0
	v_pk_add_f32 v[8:9], v[8:9], 1.0 op_sel_hi:[1,0]
	s_nop 0
	v_rcp_f32_e32 v37, v9
	s_nop 0
	v_mul_f32_e32 v9, v35, v37
	v_rcp_f32_e32 v36, v8
	s_nop 0
	v_mul_f32_e32 v38, v34, v36
	v_mov_b32_e32 v35, v38
	s_waitcnt vmcnt(0)
	v_mov_b32_e32 v32, v220
	v_mov_b32_e32 v33, v221
	v_lshlrev_b32_e32 v36, 16, v32
	v_and_b32_e32 v32, 0xffff0000, v32
	v_mov_b32_e32 v8, v35
	v_mul_f32_e32 v34, 0xbfb8aa3b, v36
	v_mul_f32_e32 v35, 0xbfb8aa3b, v32
	v_exp_f32_e32 v34, v34
	v_exp_f32_e32 v35, v35
	v_pk_mul_f32 v[126:127], v[10:11], v[8:9]
	v_pk_mul_f32 v[8:9], v[124:125], v[124:125]
	v_pk_mul_f32 v[10:11], v[126:127], v[126:127]
	v_pk_add_f32 v[34:35], v[34:35], 1.0 op_sel_hi:[1,0]
	v_add_f32_e32 v1, v10, v11
	v_rcp_f32_e32 v38, v35
	v_add_f32_e32 v2, v8, v9
	v_add_f32_e32 v1, v2, v1
	v_add_f32_e32 v0, v0, v1
	v_mul_f32_e32 v35, v32, v38
	v_rcp_f32_e32 v37, v34
	s_nop 0
	v_mul_f32_e32 v34, v36, v37
	v_lshlrev_b32_e32 v32, 16, v33
	v_and_b32_e32 v33, 0xffff0000, v33
	v_pk_mul_f32 v[128:129], v[12:13], v[34:35]
	v_mul_f32_e32 v12, 0xbfb8aa3b, v32
	v_mul_f32_e32 v13, 0xbfb8aa3b, v33
	v_exp_f32_e32 v12, v12
	v_exp_f32_e32 v13, v13
	s_nop 0
	v_pk_add_f32 v[12:13], v[12:13], 1.0 op_sel_hi:[1,0]
	s_nop 0
	v_rcp_f32_e32 v35, v13
	s_nop 0
	v_mul_f32_e32 v13, v33, v35
	v_rcp_f32_e32 v34, v12
	s_nop 0
	v_mul_f32_e32 v12, v32, v34
	v_pk_mul_f32 v[130:131], v[14:15], v[12:13]
	v_pk_mul_f32 v[12:13], v[128:129], v[128:129]
	v_pk_mul_f32 v[14:15], v[130:131], v[130:131]
	v_add_f32_e32 v2, v12, v13
	v_add_f32_e32 v1, v14, v15
	v_add_f32_e32 v1, v2, v1
	v_add_f32_e32 v0, v0, v1
	ds_bpermute_b32 v1, v139, v0
	s_and_saveexec_b64 s[0:1], s[40:41]
	s_cbranch_execz .LBB0_768
	s_waitcnt lgkmcnt(0)
	v_add_f32_e32 v0, v0, v1
	ds_write_b32 v141, v0

; DI_ bf16x8 pack8(float a0, float a1, float a2, float a3, float a4, float a5, float a6, float a7) { u32x4 p; p.x = pk2(a0, a1); p.y = pk2(a2, a3); p.z = pk2(a4, a5); p.w = pk2(a6, a7); return __builtin_bit_cast(bf16x8, p); }
; #define MFMA32(a, b, c) __builtin_amdgcn_mfma_f32_32x32x16_bf16((a), (b), (c), 0, 0, 0)
; DI_ int kvmap(int rho) { return (rho & 0x13) | ((rho & 4) << 1) | ((rho & 8) >> 1); }
; DI_ void ssd_passC(const bf16_t* xsT, const bf16_t* Btok, const bf16_t* Ctok, const bf16_t* Sc, const float* dt, const float* acum, const float* Dskip, const float* norm_w, bf16_t* Z, unsigned char* lds, int tid, int lane, int wid) {
;     ...
;             for (int sb = 0; sb <= tb; ++sb) {
;                 f32x16 cb;
; #pragma unroll
;                 for (int i = 0; i < 16; ++i) cb[i] = 0.f;
;                 const unsigned char* bp = lds + PC_B + (32 * sb + kvmap(r32)) * PC_RS + hi * 16;
; #pragma unroll
;                 for (int ks = 0; ks < 8; ++ks) cb = MFMA32(*(const bf16x8*)(bp + 32 * ks), *(const bf16x8*)(cfp + 32 * ks), cb);
;                 float m[16];
; #pragma unroll
;                 for (int q4 = 0; q4 < 4; ++q4) {
;                     const int sl0 = 32 * sb + 16 * (q4 >> 1) + 8 * hi + 4 * (q4 & 1);
;                     const f32x4 as4 = *(const f32x4*)(sa + hl * 128 + sl0), ds4 = *(const f32x4*)(sd + hl * 128 + sl0);
; #pragma unroll
;                     for (int e = 0; e < 4; ++e) { const int sl = sl0 + e; float v = cb[4 * q4 + e] * __expf(fminf(at - as4[e], 0.f)) * ds4[e]; v = (sl <= tl) ? v : 0.f; if (sl == tl) v += Dh; m[4 * q4 + e] = v; }
;                 }
;                 const bf16x8 pf0 = pack8(m[0], m[1], m[2], m[3], m[4], m[5], m[6], m[7]), pf1 = pack8(m[8], m[9], m[10], m[11], m[12], m[13], m[14], m[15]);
.LBB0_769:
	v_add_u32_e32 v159, 0, v156
	ds_read_b128 v[206:209], v159
	ds_read_b128 v[210:213], v159 offset:32
	ds_read_b128 v[214:217], v159 offset:64
	ds_read_b128 v[218:221], v159 offset:96
	ds_read_b128 v[222:225], v159 offset:128
	ds_read_b128 v[226:229], v159 offset:160
	ds_read_b128 v[230:233], v159 offset:192
	ds_read_b128 v[234:237], v159 offset:224
	v_add_u32_e32 v177, 0, v157
	v_add_u32_e32 v164, 0x22800, v177
	ds_read_b128 v[164:167], v164
	v_add_u32_e32 v160, 0x22000, v177
	ds_read_b128 v[160:163], v160
	v_add_u32_e32 v157, 0x80, v157
	s_waitcnt lgkmcnt(9)
	v_mfma_f32_32x32x16_bf16 v[32:47], v[206:209], v[50:53], 0
	v_add_u32_e32 v156, 0x2200, v156
	s_waitcnt lgkmcnt(8)
	v_mfma_f32_32x32x16_bf16 v[32:47], v[210:213], v[54:57], v[32:47]
	s_waitcnt lgkmcnt(7)
	v_mfma_f32_32x32x16_bf16 v[32:47], v[214:217], v[58:61], v[32:47]
	s_waitcnt lgkmcnt(6)
	v_mfma_f32_32x32x16_bf16 v[32:47], v[218:221], v[62:65], v[32:47]
	s_waitcnt lgkmcnt(5)
	v_mfma_f32_32x32x16_bf16 v[32:47], v[222:225], v[66:69], v[32:47]
	s_waitcnt lgkmcnt(4)
	v_mfma_f32_32x32x16_bf16 v[32:47], v[226:229], v[70:73], v[32:47]
	s_waitcnt lgkmcnt(3)
	v_mfma_f32_32x32x16_bf16 v[32:47], v[230:233], v[74:77], v[32:47]
	v_add_u32_e32 v159, s7, v137
	v_cmp_gt_u32_e32 vcc, v92, v159
	v_cmp_le_u32_e64 s[0:1], v159, v92
	v_add_u32_e32 v178, 4, v159
	s_add_i32 s7, s7, 32
	s_waitcnt lgkmcnt(2)
	v_mfma_f32_32x32x16_bf16 v[32:47], v[234:237], v[78:81], v[32:47]
	v_add_u32_e32 v222, 0x11000, v158
	ds_read_b128 v[206:209], v222
	ds_read_b128 v[210:213], v222 offset:32
	v_add_u32_e32 v222, 0x13200, v158
	ds_read_b128 v[214:217], v222
	ds_read_b128 v[218:221], v222 offset:32
	s_waitcnt lgkmcnt(0)
	v_sub_f32_e32 v160, v155, v160
	v_sub_f32_e32 v161, v155, v161
	v_min_f32_e32 v160, 0, v160
	v_min_f32_e32 v161, 0, v161
	v_mul_f32_e32 v160, 0x3fb8aa3b, v160
	v_mul_f32_e32 v161, 0x3fb8aa3b, v161
	v_exp_f32_e32 v160, v160
	v_exp_f32_e32 v161, v161
	s_nop 0
	v_mul_f32_e32 v32, v32, v160
	v_mul_f32_e32 v33, v33, v161
	v_mul_f32_e32 v32, v164, v32
	v_mul_f32_e32 v161, v165, v33
	v_add_u32_e32 v160, 1, v159
	v_cndmask_b32_e64 v33, 0, v32, s[0:1]
	v_cndmask_b32_e32 v32, 0, v161, vcc
	v_cmp_eq_u32_e32 vcc, v159, v92
	v_cmp_eq_u32_e64 s[0:1], v160, v91
	v_pk_add_f32 v[160:161], v[132:133], v[32:33]
	s_nop 0
	v_cndmask_b32_e64 v164, v32, v160, s[0:1]
	v_cndmask_b32_e32 v165, v33, v161, vcc
	v_sub_f32_e32 v32, v155, v162
	v_sub_f32_e32 v33, v155, v163
	v_min_f32_e32 v32, 0, v32
	v_min_f32_e32 v33, 0, v33
	v_mul_f32_e32 v32, 0x3fb8aa3b, v32
	v_mul_f32_e32 v33, 0x3fb8aa3b, v33
	v_exp_f32_e32 v32, v32
	v_exp_f32_e32 v33, v33
	v_or_b32_e32 v160, 3, v159
	v_or_b32_e32 v161, 2, v159
	v_cmp_le_u32_e32 vcc, v160, v91
	v_pk_mul_f32 v[32:33], v[34:35], v[32:33]
	v_cmp_eq_u32_e64 s[0:1], v160, v91
	v_pk_mul_f32 v[32:33], v[166:167], v[32:33]
	v_add_u32_e32 v160, 0x22810, v177
	v_cndmask_b32_e32 v33, 0, v33, vcc
	v_cmp_le_u32_e32 vcc, v161, v92
	s_nop 1
	v_cndmask_b32_e32 v32, 0, v32, vcc
	v_cmp_eq_u32_e32 vcc, v161, v92
	v_pk_add_f32 v[34:35], v[132:133], v[32:33]
	ds_read_b128 v[160:163], v160
	v_cndmask_b32_e32 v167, v32, v34, vcc
	v_add_u32_e32 v32, 0x22010, v177
	v_cndmask_b32_e64 v166, v33, v35, s[0:1]
	ds_read_b128 v[32:35], v32
	v_cmp_gt_u32_e32 vcc, v92, v178
	v_cmp_le_u32_e64 s[0:1], v178, v92
	s_waitcnt lgkmcnt(0)
	v_sub_f32_e32 v32, v155, v32
	v_sub_f32_e32 v33, v155, v33
	v_min_f32_e32 v32, 0, v32
	v_min_f32_e32 v33, 0, v33
	v_mul_f32_e32 v32, 0x3fb8aa3b, v32
	v_mul_f32_e32 v33, 0x3fb8aa3b, v33
	v_exp_f32_e32 v32, v32
	v_exp_f32_e32 v33, v33
	v_mul_f32_e32 v32, v36, v32
	v_mul_f32_e32 v33, v37, v33
	v_mul_f32_e32 v32, v160, v32
	v_mul_f32_e32 v37, v161, v33
	v_add_u32_e32 v36, 5, v159
	v_cndmask_b32_e64 v33, 0, v32, s[0:1]
	v_cndmask_b32_e32 v32, 0, v37, vcc
	v_cmp_eq_u32_e32 vcc, v178, v92
	v_cmp_eq_u32_e64 s[0:1], v36, v91
	v_pk_add_f32 v[36:37], v[132:133], v[32:33]
	s_nop 0
	v_cndmask_b32_e64 v160, v32, v36, s[0:1]
	v_cndmask_b32_e32 v161, v33, v37, vcc
	v_sub_f32_e32 v32, v155, v34
	v_sub_f32_e32 v33, v155, v35
	v_min_f32_e32 v32, 0, v32
	v_min_f32_e32 v33, 0, v33
	v_mul_f32_e32 v32, 0x3fb8aa3b, v32
	v_mul_f32_e32 v33, 0x3fb8aa3b, v33
	v_exp_f32_e32 v32, v32
	v_exp_f32_e32 v33, v33
	v_or_b32_e32 v34, 3, v178
	v_or_b32_e32 v35, 2, v178
	v_cmp_le_u32_e32 vcc, v34, v91
	v_pk_mul_f32 v[32:33], v[38:39], v[32:33]
	v_cmp_eq_u32_e64 s[0:1], v34, v91
	v_pk_mul_f32 v[32:33], v[162:163], v[32:33]
	v_add_u32_e32 v36, 0x22840, v177
	v_cndmask_b32_e32 v33, 0, v33, vcc
	v_cmp_le_u32_e32 vcc, v35, v92
	ds_read_b128 v[36:39], v36
	v_add_u32_e32 v178, 16, v159
	v_cndmask_b32_e32 v32, 0, v32, vcc
	v_cmp_eq_u32_e32 vcc, v35, v92
	v_pk_add_f32 v[34:35], v[132:133], v[32:33]
	s_nop 0
	v_cndmask_b32_e32 v163, v32, v34, vcc
	v_add_u32_e32 v32, 0x22040, v177
	v_cndmask_b32_e64 v162, v33, v35, s[0:1]
	ds_read_b128 v[32:35], v32
	v_cmp_gt_u32_e32 vcc, v92, v178
	v_cmp_le_u32_e64 s[0:1], v178, v92
	s_waitcnt lgkmcnt(0)
; DI_ float bf_lo(unsigned w) { return __uint_as_float(w << 16); }
; DI_ float bf_hi(unsigned w) { return __uint_as_float(w & 0xffff0000u); }
; DI_ bf16x8 pack8(float a0, float a1, float a2, float a3, float a4, float a5, float a6, float a7) { u32x4 p; p.x = pk2(a0, a1); p.y = pk2(a2, a3); p.z = pk2(a4, a5); p.w = pk2(a6, a7); return __builtin_bit_cast(bf16x8, p); }
; #define MFMA32(a, b, c) __builtin_amdgcn_mfma_f32_32x32x16_bf16((a), (b), (c), 0, 0, 0)
; DI_ float silu_f(float v) { return v / (1.f + __expf(-v)); }
; DI_ void ssd_passC(const bf16_t* xsT, const bf16_t* Btok, const bf16_t* Ctok, const bf16_t* Sc, const float* dt, const float* acum, const float* Dskip, const float* norm_w, bf16_t* Z, unsigned char* lds, int tid, int lane, int wid) {
;     ...
;                     for (int e = 0; e < 4; ++e) { const int sl = sl0 + e; float v = cb[4 * q4 + e] * __expf(fminf(at - as4[e], 0.f)) * ds4[e]; v = (sl <= tl) ? v : 0.f; if (sl == tl) v += Dh; m[4 * q4 + e] = v; }
;                 }
;                 const bf16x8 pf0 = pack8(m[0], m[1], m[2], m[3], m[4], m[5], m[6], m[7]), pf1 = pack8(m[8], m[9], m[10], m[11], m[12], m[13], m[14], m[15]);
; #pragma unroll
;                 for (int pb = 0; pb < 2; ++pb) {
;                     const unsigned char* xp = lds + PC_X + (hl * 64 + 32 * pb + r32) * PC_RS + (32 * sb + 8 * hi) * 2;
;                     yv[it][pb] = MFMA32(*(const bf16x8*)xp, pf0, yv[it][pb]); yv[it][pb] = MFMA32(*(const bf16x8*)(xp + 32), pf1, yv[it][pb]);
;                 }
;     ...
;             const int tg = t0 + tl; float sq = 0.f;
; #pragma unroll
;             for (int pb = 0; pb < 2; ++pb)
; #pragma unroll
;                 for (int q4 = 0; q4 < 4; ++q4) {
;                     const int chn = hh * 64 + 32 * pb + 8 * q4 + 4 * hi;
;                     const u32x2 zw = *(const u32x2*)(Z + (size_t)tg * DI + chn);
;                     const float a0 = yv[it][pb][4 * q4] * silu_f(bf_lo(zw.x)), a1 = yv[it][pb][4 * q4 + 1] * silu_f(bf_hi(zw.x)), a2 = yv[it][pb][4 * q4 + 2] * silu_f(bf_lo(zw.y)), a3 = yv[it][pb][4 * q4 + 3] * silu_f(bf_hi(zw.y));
;                     sq += (a0 * a0 + a1 * a1) + (a2 * a2 + a3 * a3);
;                     yv[it][pb][4 * q4] = a0; yv[it][pb][4 * q4 + 1] = a1; yv[it][pb][4 * q4 + 2] = a2; yv[it][pb][4 * q4 + 3] = a3;
	v_sub_f32_e32 v32, v155, v32
	v_sub_f32_e32 v33, v155, v33
	v_min_f32_e32 v32, 0, v32
	v_min_f32_e32 v33, 0, v33
	v_mul_f32_e32 v32, 0x3fb8aa3b, v32
	v_mul_f32_e32 v33, 0x3fb8aa3b, v33
	v_exp_f32_e32 v32, v32
	v_exp_f32_e32 v33, v33
	v_mul_f32_e32 v32, v40, v32
	v_mul_f32_e32 v33, v41, v33
	v_mul_f32_e32 v32, v36, v32
	v_mul_f32_e32 v37, v37, v33
	v_add_u32_e32 v36, 17, v159
	v_cndmask_b32_e64 v33, 0, v32, s[0:1]
	v_cndmask_b32_e32 v32, 0, v37, vcc
	v_cmp_eq_u32_e32 vcc, v178, v92
	v_cmp_eq_u32_e64 s[0:1], v36, v91
	v_pk_add_f32 v[36:37], v[132:133], v[32:33]
	s_nop 0
	v_cndmask_b32_e64 v40, v32, v36, s[0:1]
	v_cndmask_b32_e32 v41, v33, v37, vcc
	v_sub_f32_e32 v32, v155, v34
	v_sub_f32_e32 v33, v155, v35
	v_min_f32_e32 v32, 0, v32
	v_min_f32_e32 v33, 0, v33
	v_mul_f32_e32 v32, 0x3fb8aa3b, v32
	v_mul_f32_e32 v33, 0x3fb8aa3b, v33
	v_exp_f32_e32 v32, v32
	v_exp_f32_e32 v33, v33
	v_or_b32_e32 v34, 3, v178
	v_or_b32_e32 v35, 2, v178
	v_cmp_le_u32_e32 vcc, v34, v91
	v_pk_mul_f32 v[32:33], v[42:43], v[32:33]
	v_cmp_eq_u32_e64 s[0:1], v34, v91
	v_pk_mul_f32 v[32:33], v[38:39], v[32:33]
	v_add_u32_e32 v36, 0x22850, v177
	v_cndmask_b32_e32 v33, 0, v33, vcc
	v_cmp_le_u32_e32 vcc, v35, v92
	ds_read_b128 v[36:39], v36
	v_add_u32_e32 v178, 20, v159
	v_cndmask_b32_e32 v32, 0, v32, vcc
	v_cmp_eq_u32_e32 vcc, v35, v92
	v_pk_add_f32 v[34:35], v[132:133], v[32:33]
	s_nop 0
	v_cndmask_b32_e32 v43, v32, v34, vcc
	v_add_u32_e32 v32, 0x22050, v177
	v_cndmask_b32_e64 v42, v33, v35, s[0:1]
	ds_read_b128 v[32:35], v32
	v_cmp_gt_u32_e32 vcc, v92, v178
	v_cmp_le_u32_e64 s[0:1], v178, v92
	s_waitcnt lgkmcnt(0)
	v_sub_f32_e32 v32, v155, v32
	v_sub_f32_e32 v33, v155, v33
	v_min_f32_e32 v32, 0, v32
	v_min_f32_e32 v33, 0, v33
	v_mul_f32_e32 v32, 0x3fb8aa3b, v32
	v_mul_f32_e32 v33, 0x3fb8aa3b, v33
	v_exp_f32_e32 v32, v32
	v_exp_f32_e32 v33, v33
	v_mul_f32_e32 v32, v44, v32
	v_mul_f32_e32 v33, v45, v33
	v_mul_f32_e32 v32, v36, v32
	v_mul_f32_e32 v37, v37, v33
	v_add_u32_e32 v36, 21, v159
	v_cndmask_b32_e64 v33, 0, v32, s[0:1]
	v_cndmask_b32_e32 v32, 0, v37, vcc
	v_cmp_eq_u32_e32 vcc, v178, v92
	v_cmp_eq_u32_e64 s[0:1], v36, v91
	v_pk_add_f32 v[36:37], v[132:133], v[32:33]
	s_nop 0
	v_cndmask_b32_e64 v44, v32, v36, s[0:1]
	v_cndmask_b32_e32 v45, v33, v37, vcc
	v_sub_f32_e32 v32, v155, v34
	v_sub_f32_e32 v33, v155, v35
	v_min_f32_e32 v32, 0, v32
	v_min_f32_e32 v33, 0, v33
	v_mul_f32_e32 v32, 0x3fb8aa3b, v32
	v_mul_f32_e32 v33, 0x3fb8aa3b, v33
	v_exp_f32_e32 v32, v32
	v_exp_f32_e32 v33, v33
	v_or_b32_e32 v34, 3, v178
	v_or_b32_e32 v35, 2, v178
	v_cmp_le_u32_e32 vcc, v34, v91
	v_pk_mul_f32 v[32:33], v[46:47], v[32:33]
	v_cmp_eq_u32_e64 s[0:1], v34, v91
	v_pk_mul_f32 v[32:33], v[38:39], v[32:33]
	v_cvt_pk_bf16_f32 v36, v165, v164
	v_cndmask_b32_e32 v33, 0, v33, vcc
	v_cmp_le_u32_e32 vcc, v35, v92
	v_cvt_pk_bf16_f32 v37, v167, v166
	v_cvt_pk_bf16_f32 v38, v161, v160
	v_cndmask_b32_e32 v32, 0, v32, vcc
	v_cmp_eq_u32_e32 vcc, v35, v92
	v_pk_add_f32 v[34:35], v[132:133], v[32:33]
	v_cvt_pk_bf16_f32 v39, v163, v162
	v_cndmask_b32_e32 v46, v32, v34, vcc
	v_cvt_pk_bf16_f32 v34, v45, v44
	v_cvt_pk_bf16_f32 v32, v41, v40
	v_cndmask_b32_e64 v35, v33, v35, s[0:1]
	v_cvt_pk_bf16_f32 v33, v43, v42
	s_waitcnt lgkmcnt(0)
	v_mfma_f32_32x32x16_bf16 v[16:31], v[206:209], v[36:39], v[16:31]
	v_cvt_pk_bf16_f32 v35, v46, v35
	s_add_i32 s0, s19, s7
	v_add_u32_e32 v158, 64, v158
	s_cmp_lg_u32 s0, 0
	s_waitcnt lgkmcnt(0)
	v_mfma_f32_32x32x16_bf16 v[16:31], v[210:213], v[32:35], v[16:31]
	s_waitcnt lgkmcnt(0)
	v_mfma_f32_32x32x16_bf16 v[0:15], v[214:217], v[36:39], v[0:15]
	s_waitcnt lgkmcnt(0)
	v_mfma_f32_32x32x16_bf16 v[0:15], v[218:221], v[32:35], v[0:15]
	s_cbranch_scc1 .LBB0_769
	v_or_b32_e32 v32, s42, v92
	v_ashrrev_i32_e32 v33, 31, v32
	v_lshl_or_b32 v34, s6, 6, v138
	v_lshlrev_b64 v[32:33], 12, v[32:33]
	v_lshl_add_u64 v[32:33], s[56:57], 0, v[32:33]
	v_ashrrev_i32_e32 v35, 31, v34
	v_lshl_add_u64 v[46:47], v[34:35], 1, v[32:33]
	global_load_dwordx2 v[206:207], v[46:47], off
	global_load_dwordx2 v[208:209], v[46:47], off offset:16
	global_load_dwordx2 v[210:211], v[46:47], off offset:32
	global_load_dwordx2 v[212:213], v[46:47], off offset:48
	global_load_dwordx2 v[214:215], v[46:47], off offset:64
	global_load_dwordx2 v[216:217], v[46:47], off offset:80
	global_load_dwordx2 v[218:219], v[46:47], off offset:96
	global_load_dwordx2 v[220:221], v[46:47], off offset:112
	s_waitcnt vmcnt(7)
	v_mov_b32_e32 v34, v206
	v_mov_b32_e32 v35, v207
	v_lshlrev_b32_e32 v38, 16, v34
	v_and_b32_e32 v34, 0xffff0000, v34
	v_mul_f32_e32 v36, 0xbfb8aa3b, v38
	v_mul_f32_e32 v37, 0xbfb8aa3b, v34
	v_exp_f32_e32 v36, v36
	v_exp_f32_e32 v37, v37
	s_nop 0
	v_pk_add_f32 v[36:37], v[36:37], 1.0 op_sel_hi:[1,0]
	s_nop 0
	v_rcp_f32_e32 v40, v37
	s_nop 0
	v_mul_f32_e32 v37, v34, v40
	v_rcp_f32_e32 v39, v36
	s_nop 0
	v_mul_f32_e32 v36, v38, v39
	v_pk_mul_f32 v[16:17], v[16:17], v[36:37]
	v_lshlrev_b32_e32 v36, 16, v35
	v_and_b32_e32 v37, 0xffff0000, v35
	v_mul_f32_e32 v34, 0xbfb8aa3b, v36
	v_mul_f32_e32 v35, 0xbfb8aa3b, v37
	v_exp_f32_e32 v34, v34
	v_exp_f32_e32 v35, v35
	s_nop 0
	v_pk_add_f32 v[34:35], v[34:35], 1.0 op_sel_hi:[1,0]
	s_nop 0
	v_rcp_f32_e32 v39, v35
	s_nop 0
	v_mul_f32_e32 v35, v37, v39
	v_rcp_f32_e32 v38, v34
	s_nop 0
	v_mul_f32_e32 v34, v36, v38
	v_pk_mul_f32 v[18:19], v[18:19], v[34:35]
	v_pk_mul_f32 v[34:35], v[16:17], v[16:17]
	v_pk_mul_f32 v[36:37], v[18:19], v[18:19]
	v_add_f32_e32 v34, v34, v35
	v_add_f32_e32 v36, v36, v37
	v_add_f32_e32 v34, v34, v36
	s_waitcnt vmcnt(6)
; DI_ float bf_lo(unsigned w) { return __uint_as_float(w << 16); }
; DI_ float bf_hi(unsigned w) { return __uint_as_float(w & 0xffff0000u); }
; DI_ float silu_f(float v) { return v / (1.f + __expf(-v)); }
; DI_ void ssd_passC(const bf16_t* xsT, const bf16_t* Btok, const bf16_t* Ctok, const bf16_t* Sc, const float* dt, const float* acum, const float* Dskip, const float* norm_w, bf16_t* Z, unsigned char* lds, int tid, int lane, int wid) {
;     ...
;             const int tg = t0 + tl; float sq = 0.f;
; #pragma unroll
;             for (int pb = 0; pb < 2; ++pb)
; #pragma unroll
;                 for (int q4 = 0; q4 < 4; ++q4) {
;                     const int chn = hh * 64 + 32 * pb + 8 * q4 + 4 * hi;
;                     const u32x2 zw = *(const u32x2*)(Z + (size_t)tg * DI + chn);
;                     const float a0 = yv[it][pb][4 * q4] * silu_f(bf_lo(zw.x)), a1 = yv[it][pb][4 * q4 + 1] * silu_f(bf_hi(zw.x)), a2 = yv[it][pb][4 * q4 + 2] * silu_f(bf_lo(zw.y)), a3 = yv[it][pb][4 * q4 + 3] * silu_f(bf_hi(zw.y));
;                     sq += (a0 * a0 + a1 * a1) + (a2 * a2 + a3 * a3);
;                     yv[it][pb][4 * q4] = a0; yv[it][pb][4 * q4 + 1] = a1; yv[it][pb][4 * q4 + 2] = a2; yv[it][pb][4 * q4 + 3] = a3;
	v_mov_b32_e32 v38, v208
	v_mov_b32_e32 v39, v209
	v_lshlrev_b32_e32 v42, 16, v38
	v_and_b32_e32 v38, 0xffff0000, v38
	v_mul_f32_e32 v40, 0xbfb8aa3b, v42
	v_mul_f32_e32 v41, 0xbfb8aa3b, v38
	v_exp_f32_e32 v40, v40
	v_exp_f32_e32 v41, v41
	s_nop 0
	v_pk_add_f32 v[40:41], v[40:41], 1.0 op_sel_hi:[1,0]
	s_nop 0
	v_rcp_f32_e32 v44, v41
	s_nop 0
	v_mul_f32_e32 v41, v38, v44
	v_rcp_f32_e32 v43, v40
	s_nop 0
	v_mul_f32_e32 v40, v42, v43
	v_pk_mul_f32 v[20:21], v[20:21], v[40:41]
	v_lshlrev_b32_e32 v40, 16, v39
	v_and_b32_e32 v41, 0xffff0000, v39
	v_mul_f32_e32 v38, 0xbfb8aa3b, v40
	v_mul_f32_e32 v39, 0xbfb8aa3b, v41
	v_exp_f32_e32 v38, v38
	v_exp_f32_e32 v39, v39
	s_nop 0
	v_pk_add_f32 v[38:39], v[38:39], 1.0 op_sel_hi:[1,0]
	s_nop 0
	v_rcp_f32_e32 v43, v39
	s_nop 0
	v_mul_f32_e32 v39, v41, v43
	v_rcp_f32_e32 v42, v38
	s_nop 0
	v_mul_f32_e32 v38, v40, v42
	v_pk_mul_f32 v[22:23], v[22:23], v[38:39]
	v_pk_mul_f32 v[38:39], v[20:21], v[20:21]
	v_pk_mul_f32 v[40:41], v[22:23], v[22:23]
	v_add_f32_e32 v38, v38, v39
	v_add_f32_e32 v40, v40, v41
	v_add_f32_e32 v38, v38, v40
	v_add_f32_e32 v34, v34, v38
	s_waitcnt vmcnt(5)
	v_mov_b32_e32 v42, v210
	v_mov_b32_e32 v43, v211
	v_lshlrev_b32_e32 v50, 16, v42
	v_and_b32_e32 v42, 0xffff0000, v42
	v_mul_f32_e32 v44, 0xbfb8aa3b, v50
	v_mul_f32_e32 v45, 0xbfb8aa3b, v42
	v_exp_f32_e32 v44, v44
	v_exp_f32_e32 v45, v45
	s_nop 0
	v_pk_add_f32 v[44:45], v[44:45], 1.0 op_sel_hi:[1,0]
	s_nop 0
	v_rcp_f32_e32 v52, v45
	s_nop 0
	v_mul_f32_e32 v45, v42, v52
	v_rcp_f32_e32 v51, v44
	s_nop 0
	v_mul_f32_e32 v44, v50, v51
	v_pk_mul_f32 v[24:25], v[24:25], v[44:45]
	v_lshlrev_b32_e32 v44, 16, v43
	v_and_b32_e32 v45, 0xffff0000, v43
	v_mul_f32_e32 v42, 0xbfb8aa3b, v44
	v_mul_f32_e32 v43, 0xbfb8aa3b, v45
	v_exp_f32_e32 v42, v42
	v_exp_f32_e32 v43, v43
	s_nop 0
	v_pk_add_f32 v[42:43], v[42:43], 1.0 op_sel_hi:[1,0]
	s_nop 0
	v_rcp_f32_e32 v51, v43
	s_nop 0
	v_mul_f32_e32 v43, v45, v51
	v_rcp_f32_e32 v50, v42
	s_nop 0
	v_mul_f32_e32 v42, v44, v50
	v_pk_mul_f32 v[26:27], v[26:27], v[42:43]
	v_pk_mul_f32 v[42:43], v[24:25], v[24:25]
	v_pk_mul_f32 v[44:45], v[26:27], v[26:27]
	v_add_f32_e32 v36, v42, v43
	v_add_f32_e32 v35, v44, v45
	v_add_f32_e32 v35, v36, v35
	v_add_f32_e32 v34, v34, v35
	s_waitcnt vmcnt(4)
	v_mov_b32_e32 v50, v212
	v_mov_b32_e32 v51, v213
	v_lshlrev_b32_e32 v54, 16, v50
	v_and_b32_e32 v50, 0xffff0000, v50
	v_mul_f32_e32 v52, 0xbfb8aa3b, v54
	v_mul_f32_e32 v53, 0xbfb8aa3b, v50
	v_exp_f32_e32 v52, v52
	v_exp_f32_e32 v53, v53
	s_nop 0
	v_pk_add_f32 v[52:53], v[52:53], 1.0 op_sel_hi:[1,0]
	s_nop 0
	v_rcp_f32_e32 v56, v53
	s_nop 0
	v_mul_f32_e32 v53, v50, v56
	v_rcp_f32_e32 v55, v52
	s_nop 0
	v_mul_f32_e32 v52, v54, v55
	v_pk_mul_f32 v[28:29], v[28:29], v[52:53]
	v_lshlrev_b32_e32 v52, 16, v51
	v_and_b32_e32 v53, 0xffff0000, v51
	v_mul_f32_e32 v50, 0xbfb8aa3b, v52
	v_mul_f32_e32 v51, 0xbfb8aa3b, v53
	v_exp_f32_e32 v50, v50
	v_exp_f32_e32 v51, v51
	s_nop 0
	v_pk_add_f32 v[50:51], v[50:51], 1.0 op_sel_hi:[1,0]
	s_nop 0
	v_rcp_f32_e32 v55, v51
	s_nop 0
	v_mul_f32_e32 v51, v53, v55
	v_rcp_f32_e32 v54, v50
	s_nop 0
	v_mul_f32_e32 v50, v52, v54
	v_pk_mul_f32 v[30:31], v[30:31], v[50:51]
	v_pk_mul_f32 v[50:51], v[28:29], v[28:29]
	v_pk_mul_f32 v[52:53], v[30:31], v[30:31]
	v_add_f32_e32 v36, v50, v51
	v_add_f32_e32 v35, v52, v53
	v_add_f32_e32 v35, v36, v35
	v_add_f32_e32 v34, v34, v35
	s_waitcnt vmcnt(3)
	v_mov_b32_e32 v54, v214
	v_mov_b32_e32 v55, v215
	v_lshlrev_b32_e32 v58, 16, v54
	v_and_b32_e32 v54, 0xffff0000, v54
	v_mul_f32_e32 v56, 0xbfb8aa3b, v58
	v_mul_f32_e32 v57, 0xbfb8aa3b, v54
	v_exp_f32_e32 v56, v56
	v_exp_f32_e32 v57, v57
	s_nop 0
	v_pk_add_f32 v[56:57], v[56:57], 1.0 op_sel_hi:[1,0]
	s_nop 0
	v_rcp_f32_e32 v60, v57
	s_nop 0
	v_mul_f32_e32 v57, v54, v60
	v_rcp_f32_e32 v59, v56
	s_nop 0
	v_mul_f32_e32 v56, v58, v59
	v_pk_mul_f32 v[0:1], v[0:1], v[56:57]
	v_lshlrev_b32_e32 v56, 16, v55
	v_and_b32_e32 v57, 0xffff0000, v55
	v_mul_f32_e32 v54, 0xbfb8aa3b, v56
	v_mul_f32_e32 v55, 0xbfb8aa3b, v57
	v_exp_f32_e32 v54, v54
	v_exp_f32_e32 v55, v55
	s_nop 0
	v_pk_add_f32 v[54:55], v[54:55], 1.0 op_sel_hi:[1,0]
	s_nop 0
	v_rcp_f32_e32 v59, v55
	s_nop 0
	v_mul_f32_e32 v55, v57, v59
	v_rcp_f32_e32 v58, v54
	s_nop 0
	v_mul_f32_e32 v54, v56, v58
	v_pk_mul_f32 v[2:3], v[2:3], v[54:55]
	v_pk_mul_f32 v[54:55], v[0:1], v[0:1]
	v_pk_mul_f32 v[56:57], v[2:3], v[2:3]
	v_add_f32_e32 v36, v54, v55
	v_add_f32_e32 v35, v56, v57
	v_add_f32_e32 v35, v36, v35
	v_add_f32_e32 v34, v34, v35
	s_waitcnt vmcnt(2)
; DI_ float bf_lo(unsigned w) { return __uint_as_float(w << 16); }
; DI_ float bf_hi(unsigned w) { return __uint_as_float(w & 0xffff0000u); }
; DI_ float silu_f(float v) { return v / (1.f + __expf(-v)); }
; DI_ void ssd_passC(const bf16_t* xsT, const bf16_t* Btok, const bf16_t* Ctok, const bf16_t* Sc, const float* dt, const float* acum, const float* Dskip, const float* norm_w, bf16_t* Z, unsigned char* lds, int tid, int lane, int wid) {
;     ...
;             const int tg = t0 + tl; float sq = 0.f;
; #pragma unroll
;             for (int pb = 0; pb < 2; ++pb)
; #pragma unroll
;                 for (int q4 = 0; q4 < 4; ++q4) {
;                     const int chn = hh * 64 + 32 * pb + 8 * q4 + 4 * hi;
;                     const u32x2 zw = *(const u32x2*)(Z + (size_t)tg * DI + chn);
;                     const float a0 = yv[it][pb][4 * q4] * silu_f(bf_lo(zw.x)), a1 = yv[it][pb][4 * q4 + 1] * silu_f(bf_hi(zw.x)), a2 = yv[it][pb][4 * q4 + 2] * silu_f(bf_lo(zw.y)), a3 = yv[it][pb][4 * q4 + 3] * silu_f(bf_hi(zw.y));
;                     sq += (a0 * a0 + a1 * a1) + (a2 * a2 + a3 * a3);
;                     yv[it][pb][4 * q4] = a0; yv[it][pb][4 * q4 + 1] = a1; yv[it][pb][4 * q4 + 2] = a2; yv[it][pb][4 * q4 + 3] = a3;
;                 }
;             sq += __shfl_xor(sq, 32);
;             if (hi == 0) ex[hl * 128 + tl] = sq;
	v_mov_b32_e32 v58, v216
	v_mov_b32_e32 v59, v217
	v_lshlrev_b32_e32 v62, 16, v58
	v_and_b32_e32 v58, 0xffff0000, v58
	v_mul_f32_e32 v60, 0xbfb8aa3b, v62
	v_mul_f32_e32 v61, 0xbfb8aa3b, v58
	v_exp_f32_e32 v60, v60
	v_exp_f32_e32 v61, v61
	s_nop 0
	v_pk_add_f32 v[60:61], v[60:61], 1.0 op_sel_hi:[1,0]
	s_nop 0
	v_rcp_f32_e32 v64, v61
	s_nop 0
	v_mul_f32_e32 v61, v58, v64
	v_rcp_f32_e32 v63, v60
	s_nop 0
	v_mul_f32_e32 v60, v62, v63
	v_pk_mul_f32 v[4:5], v[4:5], v[60:61]
	v_lshlrev_b32_e32 v60, 16, v59
	v_and_b32_e32 v61, 0xffff0000, v59
	v_mul_f32_e32 v58, 0xbfb8aa3b, v60
	v_mul_f32_e32 v59, 0xbfb8aa3b, v61
	v_exp_f32_e32 v58, v58
	v_exp_f32_e32 v59, v59
	s_nop 0
	v_pk_add_f32 v[58:59], v[58:59], 1.0 op_sel_hi:[1,0]
	s_nop 0
	v_rcp_f32_e32 v63, v59
	s_nop 0
	v_mul_f32_e32 v59, v61, v63
	v_rcp_f32_e32 v62, v58
	s_nop 0
	v_mul_f32_e32 v58, v60, v62
	v_pk_mul_f32 v[6:7], v[6:7], v[58:59]
	v_pk_mul_f32 v[58:59], v[4:5], v[4:5]
	v_pk_mul_f32 v[60:61], v[6:7], v[6:7]
	v_add_f32_e32 v36, v58, v59
	v_add_f32_e32 v35, v60, v61
	v_add_f32_e32 v35, v36, v35
	v_add_f32_e32 v34, v34, v35
	s_waitcnt vmcnt(1)
	v_mov_b32_e32 v62, v218
	v_mov_b32_e32 v63, v219
	v_lshlrev_b32_e32 v66, 16, v62
	v_and_b32_e32 v62, 0xffff0000, v62
	v_mul_f32_e32 v64, 0xbfb8aa3b, v66
	v_mul_f32_e32 v65, 0xbfb8aa3b, v62
	v_exp_f32_e32 v64, v64
	v_exp_f32_e32 v65, v65
	s_nop 0
	v_pk_add_f32 v[64:65], v[64:65], 1.0 op_sel_hi:[1,0]
	s_nop 0
	v_rcp_f32_e32 v68, v65
	s_nop 0
	v_mul_f32_e32 v65, v62, v68
	v_rcp_f32_e32 v67, v64
	s_nop 0
	v_mul_f32_e32 v64, v66, v67
	v_pk_mul_f32 v[8:9], v[8:9], v[64:65]
	v_lshlrev_b32_e32 v64, 16, v63
	v_and_b32_e32 v65, 0xffff0000, v63
	v_mul_f32_e32 v62, 0xbfb8aa3b, v64
	v_mul_f32_e32 v63, 0xbfb8aa3b, v65
	v_exp_f32_e32 v62, v62
	v_exp_f32_e32 v63, v63
	s_nop 0
	v_pk_add_f32 v[62:63], v[62:63], 1.0 op_sel_hi:[1,0]
	s_nop 0
	v_rcp_f32_e32 v67, v63
	s_nop 0
	v_mul_f32_e32 v63, v65, v67
	v_rcp_f32_e32 v66, v62
	s_nop 0
	v_mul_f32_e32 v68, v64, v66
	v_mov_b32_e32 v65, v68
	s_waitcnt vmcnt(0)
	v_mov_b32_e32 v46, v220
	v_mov_b32_e32 v47, v221
	v_lshlrev_b32_e32 v68, 16, v46
	v_and_b32_e32 v46, 0xffff0000, v46
	v_mul_f32_e32 v66, 0xbfb8aa3b, v68
	v_mul_f32_e32 v67, 0xbfb8aa3b, v46
	v_exp_f32_e32 v66, v66
	v_exp_f32_e32 v67, v67
	v_mov_b32_e32 v62, v65
	v_pk_mul_f32 v[10:11], v[10:11], v[62:63]
	v_pk_mul_f32 v[62:63], v[8:9], v[8:9]
	v_pk_add_f32 v[66:67], v[66:67], 1.0 op_sel_hi:[1,0]
	v_pk_mul_f32 v[64:65], v[10:11], v[10:11]
	v_rcp_f32_e32 v70, v67
	v_add_f32_e32 v35, v64, v65
	v_add_f32_e32 v36, v62, v63
	v_add_f32_e32 v35, v36, v35
	v_mul_f32_e32 v67, v46, v70
	v_rcp_f32_e32 v69, v66
	v_add_f32_e32 v34, v34, v35
	v_mul_f32_e32 v66, v68, v69
	v_pk_mul_f32 v[12:13], v[12:13], v[66:67]
	v_lshlrev_b32_e32 v66, 16, v47
	v_and_b32_e32 v67, 0xffff0000, v47
	v_mul_f32_e32 v46, 0xbfb8aa3b, v66
	v_mul_f32_e32 v47, 0xbfb8aa3b, v67
	v_exp_f32_e32 v46, v46
	v_exp_f32_e32 v47, v47
	s_nop 0
	v_pk_add_f32 v[46:47], v[46:47], 1.0 op_sel_hi:[1,0]
	s_nop 0
	v_rcp_f32_e32 v69, v47
	s_nop 0
	v_mul_f32_e32 v47, v67, v69
	v_rcp_f32_e32 v68, v46
	s_nop 0
	v_mul_f32_e32 v46, v66, v68
	v_pk_mul_f32 v[14:15], v[14:15], v[46:47]
	v_pk_mul_f32 v[46:47], v[12:13], v[12:13]
	v_pk_mul_f32 v[66:67], v[14:15], v[14:15]
	v_add_f32_e32 v36, v46, v47
	v_add_f32_e32 v35, v66, v67
	v_add_f32_e32 v35, v36, v35
	v_add_f32_e32 v34, v34, v35
	ds_bpermute_b32 v35, v139, v34
	s_and_saveexec_b64 s[0:1], s[40:41]
	s_cbranch_execz .LBB0_763
	s_waitcnt lgkmcnt(0)
	v_add_f32_e32 v34, v34, v35
	ds_write_b32 v143, v34
	s_branch .LBB0_763
